# head-norm phase: row loop software-pipelined by hand to keep two iterations of loads in flight (ping-pong register sets, counted vmcnt)
# baseline (speedup 1.0000x reference)
;   __device__ __forceinline__ float* O() const { return (float*)(GAS float*)out; }
; __device__ __forceinline__ unsigned pk2(float lo, float hi) { const f32x2_t v = {lo, hi}; const bf16x2_t b = __builtin_convertvector(v, bf16x2_t); return __builtin_bit_cast(unsigned, b); }
; __device__ __forceinline__ float siluf_(float x) { return x * __builtin_amdgcn_rcpf(1.0f + __expf(-x)); }
; __device__ __forceinline__ void norm_phase(const Params& p, int layer, int bid, int nb, const int tid) {
;     ...
;   {
;     const int r0 = min(bid * 2 + (tid >> 7), MT - 1);
;     ovn = *(const uint4*)(O + (size_t)r0 * 1024 + cg8 * 8);
;     gvn = *(const uint4*)(P + (size_t)r0 * DINP + gcol + h * 64 + j0);
;     psn = *(const f32x4*)(PS + (size_t)r0 * 128 + mh * 8);
;     if (mix == 0) ps2n = *(const f32x4*)(PS + (size_t)r0 * 128 + mh * 8 + 4);
;   }
;   for (int row = bid * 2 + (tid >> 7); row < MT; row += nb * 2) {
;     const uint4 ov = ovn, gv = gvn; const f32x4 ps = psn, ps2 = ps2n;
;     {
;       const int rn = min(row + nb * 2, MT - 1);
;       ovn = *(const uint4*)(O + (size_t)rn * 1024 + cg8 * 8);
;       gvn = *(const uint4*)(P + (size_t)rn * DINP + gcol + h * 64 + j0);
;       psn = *(const f32x4*)(PS + (size_t)rn * 128 + mh * 8);
;       if (mix == 0) ps2n = *(const f32x4*)(PS + (size_t)rn * 128 + mh * 8 + 4);
;     }
;     float s1 = ps[0] + ps[2], s2 = ps[1] + ps[3];
;     if (mix == 0) { s1 += ps2[0] + ps2[2]; s2 += ps2[1] + ps2[3]; }
;     float o[8], gt[8]; unpack8(ov, o); unpack8(gv, gt);
;     float mu = 0.f, rs;
;     if (mix == 3) { mu = s1 * (1.0f / 64.0f); const float var = fmaxf(s2 * (1.0f / 64.0f) - mu * mu, 0.f); rs = rsqrtf(var + 1e-5f); }
;     else rs = rsqrtf(s2 * (1.0f / 64.0f) + 1e-6f);
;     float r[8];
; #pragma unroll
;     for (int i = 0; i < 8; ++i) r[i] = (o[i] - mu) * rs * g8[i] * siluf_(gt[i]);
;     uint4 o4; o4.x = pk2(r[0], r[1]); o4.y = pk2(r[2], r[3]); o4.z = pk2(r[4], r[5]); o4.w = pk2(r[6], r[7]);
;     *(uint4*)(O + (size_t)row * 1024 + cg8 * 8) = o4;
;   }
.LBB0_133:
	s_or_b64 exec, exec, s[2:3]
	s_movk_i32 s2, 0x4280
	v_cmp_gt_i32_e64 s[36:37], s2, v52
	s_and_saveexec_b64 s[2:3], s[36:37]
	s_cbranch_execz .LBB0_143
	v_readlane_b32 s24, v253, 21
	v_cmp_ne_u32_e64 s[36:37], 3, v13
	v_ashrrev_i32_e32 v13, 31, v12
	s_ashr_i32 s39, s38, 31
	v_readlane_b32 s25, v253, 22
	v_lshl_add_u64 v[12:13], v[12:13], 0, s[38:39]
	v_mov_b32_e32 v15, v3
	v_lshl_add_u64 v[30:31], s[24:25], 0, v[2:3]
	v_lshlrev_b64 v[12:13], 11, v[12:13]
	v_lshlrev_b32_e32 v0, 3, v28
	v_lshl_add_u64 v[14:15], v[30:31], 0, v[14:15]
	v_mov_b32_e32 v21, v3
	v_readlane_b32 s24, v253, 33
	s_lshl_b32 s34, s0, 1
	v_lshl_or_b32 v12, v28, 4, v12
	v_lshlrev_b32_e32 v0, 1, v0
	v_mov_b32_e32 v1, v3
	v_lshl_add_u64 v[44:45], v[14:15], 0, v[20:21]
	v_mov_b32_e32 v23, v3
	v_readlane_b32 s25, v253, 34
	v_lshl_add_u64 v[48:49], s[72:73], 0, v[12:13]
	s_ashr_i32 s35, s34, 31
	s_waitcnt vmcnt(0)
	v_mov_b64_e32 v[12:13], v[40:41]
	v_lshl_add_u64 v[0:1], s[72:73], 0, v[0:1]
	v_lshl_add_u64 v[46:47], s[24:25], 0, v[22:23]
	s_lshl_b64 s[40:41], s[34:35], 11
	s_mov_b64 s[42:43], 0
	v_mov_b64_e32 v[14:15], v[42:43]
	v_add_u32_e32 v52, s34, v52
	v_min_i32_e32 v28, 0x427f, v52
	v_ashrrev_i32_e32 v29, 31, v28
	v_lshlrev_b64 v[20:21], 11, v[28:29]
	v_lshl_add_u64 v[30:31], v[0:1], 0, v[20:21]
	v_mad_i64_i32 v[20:21], s[24:25], v28, s68, v[44:45]
	v_lshlrev_b64 v[28:29], 9, v[28:29]
	global_load_dwordx4 v[20:23], v[20:21], off
	v_lshl_add_u64 v[50:51], v[46:47], 0, v[28:29]
	global_load_dwordx4 v[32:35], v[30:31], off
	s_nop 0
	global_load_dwordx4 v[28:31], v[50:51], off
	global_load_dwordx4 v[12:15], v[50:51], off offset:16
	global_load_dword v201, v[0:1], off
	s_branch .Lnormb_136
.Lnormb_135:
	s_or_b64 exec, exec, s[38:39]
	v_mul_f32_e32 v43, 0x4b800000, v51
	v_cmp_gt_f32_e64 s[38:39], s92, v51
	v_lshlrev_b32_e32 v40, 16, v16
	v_and_b32_e32 v41, 0xffff0000, v16
	v_cndmask_b32_e64 v43, v51, v43, s[38:39]
	v_rsq_f32_e32 v50, v43
	v_mul_f32_e32 v53, 0xbfb8aa3b, v40
	v_exp_f32_e32 v53, v53
	v_mul_f32_e32 v54, 0xbfb8aa3b, v41
	v_exp_f32_e32 v55, v54
	v_mul_f32_e32 v51, 0x45800000, v50
	v_lshlrev_b32_e32 v36, 16, v24
	v_and_b32_e32 v37, 0xffff0000, v24
	v_cndmask_b32_e64 v50, v50, v51, s[38:39]
	v_add_f32_e32 v51, 1.0, v53
	v_lshlrev_b32_e32 v16, 16, v17
	v_and_b32_e32 v17, 0xffff0000, v17
	v_rcp_f32_e32 v54, v51
	v_add_f32_e32 v51, 1.0, v55
	v_pk_add_f32 v[36:37], v[36:37], v[2:3] op_sel_hi:[1,0] neg_lo:[0,1] neg_hi:[0,1]
	v_rcp_f32_e32 v55, v51
	v_pk_mul_f32 v[36:37], v[36:37], v[50:51] op_sel_hi:[1,0]
	v_mul_f32_e32 v51, 0xbfb8aa3b, v16
	v_mul_f32_e32 v53, 0xbfb8aa3b, v17
	v_exp_f32_e32 v51, v51
	v_exp_f32_e32 v53, v53
	v_pk_mul_f32 v[36:37], v[8:9], v[36:37]
	v_pk_mul_f32 v[40:41], v[54:55], v[40:41]
	v_lshlrev_b32_e32 v42, 16, v18
	v_pk_mul_f32 v[36:37], v[40:41], v[36:37]
	v_add_f32_e32 v40, 1.0, v51
	v_add_f32_e32 v41, 1.0, v53
	v_rcp_f32_e32 v40, v40
	v_rcp_f32_e32 v41, v41
	v_and_b32_e32 v43, 0xffff0000, v18
	v_lshlrev_b32_e32 v24, 16, v25
	v_and_b32_e32 v25, 0xffff0000, v25
	v_pk_mul_f32 v[16:17], v[40:41], v[16:17]
	v_mul_f32_e32 v40, 0xbfb8aa3b, v42
	v_mul_f32_e32 v41, 0xbfb8aa3b, v43
	v_exp_f32_e32 v40, v40
	v_exp_f32_e32 v41, v41
	v_pk_add_f32 v[24:25], v[24:25], v[2:3] op_sel_hi:[1,0] neg_lo:[0,1] neg_hi:[0,1]
	v_lshlrev_b32_e32 v18, 16, v19
	v_pk_mul_f32 v[24:25], v[24:25], v[50:51] op_sel_hi:[1,0]
	v_and_b32_e32 v19, 0xffff0000, v19
	v_pk_mul_f32 v[24:25], v[10:11], v[24:25]
	v_lshlrev_b32_e32 v38, 16, v26
	v_pk_mul_f32 v[24:25], v[16:17], v[24:25]
	v_add_f32_e32 v16, 1.0, v40
	v_add_f32_e32 v17, 1.0, v41
	v_rcp_f32_e32 v16, v16
	v_rcp_f32_e32 v17, v17
	v_mul_f32_e32 v40, 0xbfb8aa3b, v18
	v_mul_f32_e32 v41, 0xbfb8aa3b, v19
	v_and_b32_e32 v39, 0xffff0000, v26
	v_exp_f32_e32 v40, v40
	v_exp_f32_e32 v41, v41
	v_pk_add_f32 v[38:39], v[38:39], v[2:3] op_sel_hi:[1,0] neg_lo:[0,1] neg_hi:[0,1]
	v_pk_mul_f32 v[16:17], v[16:17], v[42:43]
	v_pk_mul_f32 v[38:39], v[38:39], v[50:51] op_sel_hi:[1,0]
	v_lshlrev_b32_e32 v26, 16, v27
	v_pk_mul_f32 v[38:39], v[4:5], v[38:39]
	v_and_b32_e32 v27, 0xffff0000, v27
	v_pk_mul_f32 v[38:39], v[16:17], v[38:39]
	v_add_f32_e32 v16, 1.0, v40
	v_add_f32_e32 v17, 1.0, v41
	v_rcp_f32_e32 v16, v16
	v_rcp_f32_e32 v17, v17
	v_pk_add_f32 v[26:27], v[26:27], v[2:3] op_sel_hi:[1,0] neg_lo:[0,1] neg_hi:[0,1]
	v_subrev_u32_e32 v200, s34, v52
	v_cmp_lt_i32_e64 s[38:39], s94, v200
	v_pk_mul_f32 v[26:27], v[26:27], v[50:51] op_sel_hi:[1,0]
	v_pk_mul_f32 v[16:17], v[16:17], v[18:19]
	v_pk_mul_f32 v[26:27], v[6:7], v[26:27]
	v_cvt_pk_bf16_f32 v18, v38, v39
	v_pk_mul_f32 v[26:27], v[16:17], v[26:27]
	v_cvt_pk_bf16_f32 v16, v36, v37
	v_cvt_pk_bf16_f32 v17, v24, v25
	v_cvt_pk_bf16_f32 v19, v26, v27
	global_store_dwordx4 v[48:49], v[16:19], off
	s_waitcnt vmcnt(6)
	v_mov_b64_e32 v[24:25], v[32:33]
	v_mov_b64_e32 v[38:39], v[30:31]
	v_mov_b64_e32 v[16:17], v[20:21]
	v_mov_b64_e32 v[42:43], v[14:15]
	v_lshl_add_u64 v[48:49], v[48:49], 0, s[40:41]
	s_or_b64 s[42:43], s[38:39], s[42:43]
	v_mov_b64_e32 v[26:27], v[34:35]
	v_mov_b64_e32 v[18:19], v[22:23]
	v_mov_b64_e32 v[36:37], v[28:29]
	v_mov_b64_e32 v[40:41], v[12:13]
	s_andn2_b64 exec, exec, s[42:43]
	s_cbranch_execz .LBB0_143
	s_branch .Lnorma_136
;   __device__ __forceinline__ float* O() const { return (float*)(GAS float*)out; }
; __device__ __forceinline__ unsigned pk2(float lo, float hi) { const f32x2_t v = {lo, hi}; const bf16x2_t b = __builtin_convertvector(v, bf16x2_t); return __builtin_bit_cast(unsigned, b); }
; __device__ __forceinline__ float siluf_(float x) { return x * __builtin_amdgcn_rcpf(1.0f + __expf(-x)); }
; __device__ __forceinline__ void norm_phase(const Params& p, int layer, int bid, int nb, const int tid) {
;     ...
;   for (int row = bid * 2 + (tid >> 7); row < MT; row += nb * 2) {
;     const uint4 ov = ovn, gv = gvn; const f32x4 ps = psn, ps2 = ps2n;
;     {
;       const int rn = min(row + nb * 2, MT - 1);
;       ovn = *(const uint4*)(O + (size_t)rn * 1024 + cg8 * 8);
;       gvn = *(const uint4*)(P + (size_t)rn * DINP + gcol + h * 64 + j0);
;       psn = *(const f32x4*)(PS + (size_t)rn * 128 + mh * 8);
;       if (mix == 0) ps2n = *(const f32x4*)(PS + (size_t)rn * 128 + mh * 8 + 4);
;     }
;     float s1 = ps[0] + ps[2], s2 = ps[1] + ps[3];
;     if (mix == 0) { s1 += ps2[0] + ps2[2]; s2 += ps2[1] + ps2[3]; }
;     float o[8], gt[8]; unpack8(ov, o); unpack8(gv, gt);
;     float mu = 0.f, rs;
;     if (mix == 3) { mu = s1 * (1.0f / 64.0f); const float var = fmaxf(s2 * (1.0f / 64.0f) - mu * mu, 0.f); rs = rsqrtf(var + 1e-5f); }
;     else rs = rsqrtf(s2 * (1.0f / 64.0f) + 1e-6f);
;     float r[8];
; #pragma unroll
;     for (int i = 0; i < 8; ++i) r[i] = (o[i] - mu) * rs * g8[i] * siluf_(gt[i]);
;     uint4 o4; o4.x = pk2(r[0], r[1]); o4.y = pk2(r[2], r[3]); o4.z = pk2(r[4], r[5]); o4.w = pk2(r[6], r[7]);
;     *(uint4*)(O + (size_t)row * 1024 + cg8 * 8) = o4;
;   }
.Lnormb_136:
	v_add_u32_e32 v52, s34, v52
	v_min_i32_e32 v192, 0x427f, v52
	v_ashrrev_i32_e32 v193, 31, v192
	v_lshlrev_b64 v[184:185], 11, v[192:193]
	v_lshl_add_u64 v[194:195], v[0:1], 0, v[184:185]
	v_mad_i64_i32 v[184:185], s[24:25], v192, s68, v[44:45]
	v_lshlrev_b64 v[192:193], 9, v[192:193]
	global_load_dwordx4 v[184:187], v[184:185], off
	v_lshl_add_u64 v[50:51], v[46:47], 0, v[192:193]
	global_load_dwordx4 v[188:191], v[194:195], off
	s_nop 0
	global_load_dwordx4 v[192:195], v[50:51], off
	global_load_dwordx4 v[196:199], v[50:51], off offset:16
	v_add_f32_e32 v2, v37, v39
	v_add_f32_e32 v37, v41, v43
	v_add_f32_e32 v37, v2, v37
	v_cndmask_b32_e32 v50, v2, v37, vcc
	s_and_saveexec_b64 s[24:25], s[36:37]
	s_xor_b64 s[38:39], exec, s[24:25]
	v_mov_b32_e32 v2, 0x358637bd
	v_fmamk_f32 v51, v50, 0x3c800000, v2
	s_or_saveexec_b64 s[38:39], s[38:39]
	v_mov_b32_e32 v2, 0
	s_xor_b64 exec, exec, s[38:39]
	s_cbranch_execz .Lnormb_135
	v_mov_b32_e32 v37, v40
	v_mov_b32_e32 v39, v42
	v_pk_add_f32 v[36:37], v[36:37], v[38:39]
	s_mov_b32 s24, 0x3c800000
	v_add_f32_e32 v2, v36, v37
	v_cndmask_b32_e32 v51, v36, v2, vcc
	v_pk_mul_f32 v[36:37], v[50:51], s[24:25] op_sel_hi:[1,0]
	s_nop 0
	v_fma_f32 v2, -v37, v37, v36
	v_max_f32_e32 v2, 0, v2
	v_add_f32_e32 v51, 0x3727c5ac, v2
	v_mov_b32_e32 v2, v37
	s_branch .Lnormb_135
.Lnorma_135:
	s_or_b64 exec, exec, s[38:39]
	v_mul_f32_e32 v43, 0x4b800000, v51
	v_cmp_gt_f32_e64 s[38:39], s92, v51
	v_lshlrev_b32_e32 v40, 16, v16
	v_and_b32_e32 v41, 0xffff0000, v16
	v_cndmask_b32_e64 v43, v51, v43, s[38:39]
	v_rsq_f32_e32 v50, v43
	v_mul_f32_e32 v53, 0xbfb8aa3b, v40
	v_exp_f32_e32 v53, v53
	v_mul_f32_e32 v54, 0xbfb8aa3b, v41
	v_exp_f32_e32 v55, v54
	v_mul_f32_e32 v51, 0x45800000, v50
	v_lshlrev_b32_e32 v36, 16, v24
	v_and_b32_e32 v37, 0xffff0000, v24
	v_cndmask_b32_e64 v50, v50, v51, s[38:39]
	v_add_f32_e32 v51, 1.0, v53
	v_lshlrev_b32_e32 v16, 16, v17
	v_and_b32_e32 v17, 0xffff0000, v17
	v_rcp_f32_e32 v54, v51
	v_add_f32_e32 v51, 1.0, v55
	v_pk_add_f32 v[36:37], v[36:37], v[2:3] op_sel_hi:[1,0] neg_lo:[0,1] neg_hi:[0,1]
	v_rcp_f32_e32 v55, v51
	v_pk_mul_f32 v[36:37], v[36:37], v[50:51] op_sel_hi:[1,0]
	v_mul_f32_e32 v51, 0xbfb8aa3b, v16
	v_mul_f32_e32 v53, 0xbfb8aa3b, v17
	v_exp_f32_e32 v51, v51
	v_exp_f32_e32 v53, v53
	v_pk_mul_f32 v[36:37], v[8:9], v[36:37]
	v_pk_mul_f32 v[40:41], v[54:55], v[40:41]
	v_lshlrev_b32_e32 v42, 16, v18
	v_pk_mul_f32 v[36:37], v[40:41], v[36:37]
	v_add_f32_e32 v40, 1.0, v51
	v_add_f32_e32 v41, 1.0, v53
	v_rcp_f32_e32 v40, v40
	v_rcp_f32_e32 v41, v41
	v_and_b32_e32 v43, 0xffff0000, v18
	v_lshlrev_b32_e32 v24, 16, v25
	v_and_b32_e32 v25, 0xffff0000, v25
	v_pk_mul_f32 v[16:17], v[40:41], v[16:17]
	v_mul_f32_e32 v40, 0xbfb8aa3b, v42
	v_mul_f32_e32 v41, 0xbfb8aa3b, v43
	v_exp_f32_e32 v40, v40
	v_exp_f32_e32 v41, v41
	v_pk_add_f32 v[24:25], v[24:25], v[2:3] op_sel_hi:[1,0] neg_lo:[0,1] neg_hi:[0,1]
	v_lshlrev_b32_e32 v18, 16, v19
	v_pk_mul_f32 v[24:25], v[24:25], v[50:51] op_sel_hi:[1,0]
	v_and_b32_e32 v19, 0xffff0000, v19
	v_pk_mul_f32 v[24:25], v[10:11], v[24:25]
	v_lshlrev_b32_e32 v38, 16, v26
	v_pk_mul_f32 v[24:25], v[16:17], v[24:25]
	v_add_f32_e32 v16, 1.0, v40
	v_add_f32_e32 v17, 1.0, v41
	v_rcp_f32_e32 v16, v16
	v_rcp_f32_e32 v17, v17
	v_mul_f32_e32 v40, 0xbfb8aa3b, v18
	v_mul_f32_e32 v41, 0xbfb8aa3b, v19
	v_and_b32_e32 v39, 0xffff0000, v26
	v_exp_f32_e32 v40, v40
	v_exp_f32_e32 v41, v41
	v_pk_add_f32 v[38:39], v[38:39], v[2:3] op_sel_hi:[1,0] neg_lo:[0,1] neg_hi:[0,1]
	v_pk_mul_f32 v[16:17], v[16:17], v[42:43]
	v_pk_mul_f32 v[38:39], v[38:39], v[50:51] op_sel_hi:[1,0]
	v_lshlrev_b32_e32 v26, 16, v27
	v_pk_mul_f32 v[38:39], v[4:5], v[38:39]
	v_and_b32_e32 v27, 0xffff0000, v27
	v_pk_mul_f32 v[38:39], v[16:17], v[38:39]
	v_add_f32_e32 v16, 1.0, v40
	v_add_f32_e32 v17, 1.0, v41
	v_rcp_f32_e32 v16, v16
	v_rcp_f32_e32 v17, v17
	v_pk_add_f32 v[26:27], v[26:27], v[2:3] op_sel_hi:[1,0] neg_lo:[0,1] neg_hi:[0,1]
	v_subrev_u32_e32 v200, s34, v52
	v_cmp_lt_i32_e64 s[38:39], s94, v200
	v_pk_mul_f32 v[26:27], v[26:27], v[50:51] op_sel_hi:[1,0]
	v_pk_mul_f32 v[16:17], v[16:17], v[18:19]
	v_pk_mul_f32 v[26:27], v[6:7], v[26:27]
	v_cvt_pk_bf16_f32 v18, v38, v39
	v_pk_mul_f32 v[26:27], v[16:17], v[26:27]
	v_cvt_pk_bf16_f32 v16, v36, v37
	v_cvt_pk_bf16_f32 v17, v24, v25
	v_cvt_pk_bf16_f32 v19, v26, v27
	global_store_dwordx4 v[48:49], v[16:19], off
	s_waitcnt vmcnt(6)
	v_mov_b64_e32 v[24:25], v[188:189]
	v_mov_b64_e32 v[38:39], v[194:195]
	v_mov_b64_e32 v[16:17], v[184:185]
	v_mov_b64_e32 v[42:43], v[198:199]
	v_lshl_add_u64 v[48:49], v[48:49], 0, s[40:41]
	s_or_b64 s[42:43], s[38:39], s[42:43]
	v_mov_b64_e32 v[26:27], v[190:191]
	v_mov_b64_e32 v[18:19], v[186:187]
	v_mov_b64_e32 v[36:37], v[192:193]
	v_mov_b64_e32 v[40:41], v[196:197]
	s_andn2_b64 exec, exec, s[42:43]
	s_cbranch_execz .LBB0_143
	s_branch .Lnormb_136
.Lnorma_136:
	v_add_u32_e32 v52, s34, v52
	v_min_i32_e32 v28, 0x427f, v52
	v_ashrrev_i32_e32 v29, 31, v28
	v_lshlrev_b64 v[20:21], 11, v[28:29]
	v_lshl_add_u64 v[30:31], v[0:1], 0, v[20:21]
	v_mad_i64_i32 v[20:21], s[24:25], v28, s68, v[44:45]
	v_lshlrev_b64 v[28:29], 9, v[28:29]
	global_load_dwordx4 v[20:23], v[20:21], off
	v_lshl_add_u64 v[50:51], v[46:47], 0, v[28:29]
	global_load_dwordx4 v[32:35], v[30:31], off
	s_nop 0
	global_load_dwordx4 v[28:31], v[50:51], off
	global_load_dwordx4 v[12:15], v[50:51], off offset:16
	v_add_f32_e32 v2, v37, v39
	v_add_f32_e32 v37, v41, v43
	v_add_f32_e32 v37, v2, v37
	v_cndmask_b32_e32 v50, v2, v37, vcc
	s_and_saveexec_b64 s[24:25], s[36:37]
	s_xor_b64 s[38:39], exec, s[24:25]
	v_mov_b32_e32 v2, 0x358637bd
	v_fmamk_f32 v51, v50, 0x3c800000, v2
	s_or_saveexec_b64 s[38:39], s[38:39]
	v_mov_b32_e32 v2, 0
	s_xor_b64 exec, exec, s[38:39]
	s_cbranch_execz .Lnorma_135
	v_mov_b32_e32 v37, v40
	v_mov_b32_e32 v39, v42
	v_pk_add_f32 v[36:37], v[36:37], v[38:39]
	s_mov_b32 s24, 0x3c800000
	v_add_f32_e32 v2, v36, v37
	v_cndmask_b32_e32 v51, v36, v2, vcc
	v_pk_mul_f32 v[36:37], v[50:51], s[24:25] op_sel_hi:[1,0]
	s_nop 0
	v_fma_f32 v2, -v37, v37, v36
	v_max_f32_e32 v2, 0, v2
	v_add_f32_e32 v51, 0x3727c5ac, v2
	v_mov_b32_e32 v2, v37
	s_branch .Lnorma_135
